# attention steady loop: second V piece via inst offset 128 (one 64-bit address add less per step), m0 nops filled
# baseline (speedup 1.0000x reference)
.LBB0_264:
	s_waitcnt lgkmcnt(0)
	v_mfma_f32_32x32x16_bf16 v[144:159], v[220:223], v[184:187], v[80:95]
	v_add_f32_e32 v2, v112, v113
	v_add_f32_e32 v2, v114, v2
	v_add_f32_e32 v2, v115, v2
	s_lshl_b32 s2, s2, 1
	v_add_f32_e32 v2, v116, v2
	v_add_u32_e32 v0, s2, v233
	v_add_f32_e32 v2, v117, v2
	v_cvt_pk_bf16_f32 v188, v112, v113
	v_cvt_pk_bf16_f32 v189, v114, v115
	v_mfma_f32_32x32x16_bf16 v[128:143], v[216:219], v[184:187], v[80:95]
	v_add_f32_e32 v2, v118, v2
	v_add_f32_e32 v2, v119, v2
	v_add_f32_e32 v2, v120, v2
	v_add_f32_e32 v2, v121, v2
	v_cvt_pk_bf16_f32 v190, v116, v117
	v_cvt_pk_bf16_f32 v191, v118, v119
	v_mfma_f32_32x32x16_bf16 v[144:159], v[212:215], v[176:179], v[144:159]
	v_add_f32_e32 v2, v122, v2
	v_add_f32_e32 v2, v123, v2
	v_add_f32_e32 v2, v124, v2
	v_add_f32_e32 v2, v125, v2
	v_cvt_pk_bf16_f32 v180, v120, v121
	v_cvt_pk_bf16_f32 v181, v122, v123
	v_mfma_f32_32x32x16_bf16 v[128:143], v[208:211], v[176:179], v[128:143]
	v_add_f32_e32 v2, v126, v2
	v_add_f32_e32 v2, v127, v2
	v_add_f32_e32 v2, v96, v2
	v_add_f32_e32 v2, v97, v2
	v_cvt_pk_bf16_f32 v182, v124, v125
	v_cvt_pk_bf16_f32 v183, v126, v127
	v_mfma_f32_32x32x16_bf16 v[144:159], v[204:207], v[172:175], v[144:159]
	v_add_f32_e32 v2, v98, v2
	v_add_f32_e32 v2, v99, v2
	v_add_f32_e32 v2, v100, v2
	v_add_f32_e32 v2, v101, v2
	v_cvt_pk_bf16_f32 v168, v96, v97
	v_cvt_pk_bf16_f32 v169, v98, v99
	v_mfma_f32_32x32x16_bf16 v[128:143], v[200:203], v[172:175], v[128:143]
	v_add_f32_e32 v2, v102, v2
	v_add_f32_e32 v2, v103, v2
	v_add_f32_e32 v2, v104, v2
	v_add_f32_e32 v2, v105, v2
	v_cvt_pk_bf16_f32 v170, v100, v101
	v_cvt_pk_bf16_f32 v171, v102, v103
	v_mfma_f32_32x32x16_bf16 v[144:159], v[196:199], v[164:167], v[144:159]
	v_add_f32_e32 v2, v106, v2
	v_add_f32_e32 v2, v107, v2
	v_add_f32_e32 v2, v108, v2
	v_add_f32_e32 v2, v109, v2
	v_cvt_pk_bf16_f32 v160, v104, v105
	v_cvt_pk_bf16_f32 v161, v106, v107
	v_mfma_f32_32x32x16_bf16 v[128:143], v[192:195], v[164:167], v[128:143]
	v_add_f32_e32 v2, v110, v2
	v_add_f32_e32 v102, v111, v2
	v_cvt_pk_bf16_f32 v162, v108, v109
	v_cvt_pk_bf16_f32 v163, v110, v111
	ds_read_b64_tr_b16 v[96:97], v0 offset:24576
	ds_read_b64_tr_b16 v[98:99], v0 offset:25088
	ds_read_b64_tr_b16 v[10:11], v0 offset:28672
	ds_read_b64_tr_b16 v[12:13], v0 offset:29184
	ds_read_b64_tr_b16 v[6:7], v0 offset:32768
	ds_read_b64_tr_b16 v[8:9], v0 offset:33280
	ds_read_b64_tr_b16 v[2:3], v0 offset:36864
	ds_read_b64_tr_b16 v[4:5], v0 offset:37376
	v_lshl_add_u64 v[208:209], v[238:239], 0, s[54:55]
	s_add_i32 s2, s4, s22
	s_mov_b32 m0, s2
	v_lshl_add_u64 v[14:15], v[208:209], 0, s[74:75]
	global_load_lds_dwordx4 v[14:15], off
	s_lshl_b32 s2, s96, 1
	v_lshl_add_u64 v[14:15], v[242:243], 0, s[54:55]
	s_add_i32 s2, s2, s23
	s_mov_b32 m0, s2
	v_lshl_add_u64 v[100:101], v[14:15], 0, s[66:67]
	global_load_lds_dwordx4 v[100:101], off
	s_addk_i32 s2, 0x1f80
	s_mov_b32 m0, s2
	s_nop 0
	global_load_lds_dwordx4 v[100:101], off offset:128
	v_max_f32_e32 v100, v144, v145
	v_max3_f32 v101, v146, v147, v129
	v_max3_f32 v100, v100, v128, v130
	v_max3_f32 v100, v100, v131, v148
	v_max3_f32 v101, v101, v150, v151
	v_max3_f32 v100, v100, v149, v132
	v_max3_f32 v101, v101, v134, v135
	v_max3_f32 v100, v100, v133, v152
	v_max3_f32 v101, v101, v154, v155
	v_max3_f32 v100, v100, v153, v136
	v_max3_f32 v101, v101, v138, v139
	v_max3_f32 v100, v100, v137, v156
	v_max3_f32 v101, v101, v158, v159
	v_max3_f32 v100, v100, v157, v140
	v_max3_f32 v101, v101, v142, v143
	v_max3_f32 v100, v100, v141, v101
	v_mov_b32_e32 v101, v100
	s_nop 1
	v_permlane32_swap_b32_e32 v100, v101
	v_max_f32_e32 v100, v100, v101
	v_cmp_lt_f32_e32 vcc, s11, v100
	s_cmp_lg_u64 vcc, 0
	v_add_f32_e32 v210, v235, v102
	s_cselect_b64 s[46:47], -1, 0
	s_cbranch_vccnz .LBB0_272

.LBB0_267:
	s_add_i32 s2, s96, 0x2000
	s_cmpk_lg_i32 s96, 0x4000
	s_cselect_b32 s24, s2, 0
	v_mfma_f32_32x32x16_bf16 v[112:127], v[96:99], v[184:187], v[80:95]
	v_add_f32_e32 v100, v144, v145
	v_add_f32_e32 v100, v146, v100
	v_add_f32_e32 v100, v147, v100
	s_lshl_b32 s2, s4, 1
	v_add_f32_e32 v100, v148, v100
	v_add_u32_e32 v229, s2, v233
	v_add_f32_e32 v96, v149, v100
	v_cvt_pk_bf16_f32 v188, v144, v145
	v_cvt_pk_bf16_f32 v189, v146, v147
	s_nop 0
	v_add_f32_e32 v96, v150, v96
	v_add_f32_e32 v96, v151, v96
	v_add_f32_e32 v96, v152, v96
	v_add_f32_e32 v144, v153, v96
	v_mfma_f32_32x32x16_bf16 v[96:111], v[200:203], v[184:187], v[80:95]
	v_cvt_pk_bf16_f32 v190, v148, v149
	v_cvt_pk_bf16_f32 v191, v150, v151
	v_mfma_f32_32x32x16_bf16 v[112:127], v[204:207], v[176:179], v[112:127]
	v_add_f32_e32 v144, v154, v144
	v_add_f32_e32 v144, v155, v144
	v_add_f32_e32 v144, v156, v144
	v_add_f32_e32 v144, v157, v144
	v_cvt_pk_bf16_f32 v180, v152, v153
	v_cvt_pk_bf16_f32 v181, v154, v155
	v_mfma_f32_32x32x16_bf16 v[96:111], v[196:199], v[176:179], v[96:111]
	v_add_f32_e32 v144, v158, v144
	v_add_f32_e32 v144, v159, v144
	v_add_f32_e32 v144, v128, v144
	v_add_f32_e32 v144, v129, v144
	v_cvt_pk_bf16_f32 v182, v156, v157
	v_cvt_pk_bf16_f32 v183, v158, v159
	v_mfma_f32_32x32x16_bf16 v[112:127], v[192:195], v[172:175], v[112:127]
	v_add_f32_e32 v144, v130, v144
	v_add_f32_e32 v144, v131, v144
	v_add_f32_e32 v144, v132, v144
	v_add_f32_e32 v144, v133, v144
	v_cvt_pk_bf16_f32 v168, v128, v129
	v_cvt_pk_bf16_f32 v169, v130, v131
	v_mfma_f32_32x32x16_bf16 v[96:111], v[10:13], v[172:175], v[96:111]
	v_add_f32_e32 v10, v134, v144
	v_add_f32_e32 v10, v135, v10
	v_add_f32_e32 v10, v136, v10
	v_add_f32_e32 v10, v137, v10
	v_cvt_pk_bf16_f32 v170, v132, v133
	v_cvt_pk_bf16_f32 v171, v134, v135
	v_mfma_f32_32x32x16_bf16 v[112:127], v[6:9], v[164:167], v[112:127]
	v_add_f32_e32 v6, v138, v10
	v_add_f32_e32 v6, v139, v6
	v_add_f32_e32 v6, v140, v6
	v_add_f32_e32 v6, v141, v6
	v_cvt_pk_bf16_f32 v160, v136, v137
	v_cvt_pk_bf16_f32 v161, v138, v139
	v_mfma_f32_32x32x16_bf16 v[96:111], v[2:5], v[164:167], v[96:111]
	v_add_f32_e32 v2, v142, v6
	v_add_f32_e32 v134, v143, v2
	v_cvt_pk_bf16_f32 v162, v140, v141
	v_cvt_pk_bf16_f32 v163, v142, v143
	ds_read_b64_tr_b16 v[128:129], v229 offset:24576
	ds_read_b64_tr_b16 v[130:131], v229 offset:25088
	ds_read_b64_tr_b16 v[10:11], v229 offset:28672
	ds_read_b64_tr_b16 v[12:13], v229 offset:29184
	ds_read_b64_tr_b16 v[6:7], v229 offset:32768
	ds_read_b64_tr_b16 v[8:9], v229 offset:33280
	ds_read_b64_tr_b16 v[2:3], v229 offset:36864
	ds_read_b64_tr_b16 v[4:5], v229 offset:37376
	s_mov_b64 s[2:3], 0xa0000
	v_lshl_add_u64 v[132:133], v[208:209], 0, s[2:3]
	s_add_i32 s2, s96, s22
	s_mov_b32 m0, s2
	s_mov_b64 s[2:3], 0xfe60000
	global_load_lds_dwordx4 v[132:133], off
	v_lshl_add_u64 v[132:133], v[14:15], 0, s[2:3]
	s_lshl_b32 s2, s24, 1
	s_add_i32 s4, s2, s23
	s_mov_b32 m0, s4
	s_add_i32 s2, s4, 0x1f80
	global_load_lds_dwordx4 v[132:133], off
	s_mov_b32 m0, s2
	s_nop 0
	global_load_lds_dwordx4 v[132:133], off offset:128
	v_max_f32_e32 v14, v112, v113
	v_max3_f32 v15, v114, v115, v97
	v_max3_f32 v14, v14, v96, v98
	v_max3_f32 v14, v14, v99, v116
	v_max3_f32 v15, v15, v118, v119
	v_max3_f32 v14, v14, v117, v100
	v_max3_f32 v15, v15, v102, v103
	v_max3_f32 v14, v14, v101, v120
	v_max3_f32 v15, v15, v122, v123
	v_max3_f32 v14, v14, v121, v104
	v_max3_f32 v15, v15, v106, v107
	v_max3_f32 v14, v14, v105, v124
	v_max3_f32 v15, v15, v126, v127
	v_max3_f32 v14, v14, v125, v108
	v_max3_f32 v15, v15, v110, v111
	v_max3_f32 v14, v14, v109, v15
	v_mov_b32_e32 v15, v14
	s_nop 1
	v_permlane32_swap_b32_e32 v14, v15
	v_max_f32_e32 v14, v14, v15
	v_cmp_lt_f32_e32 vcc, s11, v14
	s_cmp_lg_u64 vcc, 0
	v_add_f32_e32 v235, v210, v134
	s_cselect_b64 s[46:47], -1, 0
	s_cbranch_vccnz .LBB0_275
